# barrier: followers poll the top generation word directly (skip per-XCD generation hop) + leader bumps XGEN before invalidate
# speedup vs baseline: 1.0047x; 1.0030x over previous
; __device__ __forceinline__ unsigned xb_ld(unsigned* p)              { return __hip_atomic_load(p, __ATOMIC_RELAXED, __HIP_MEMORY_SCOPE_AGENT); }
; __device__ __forceinline__ unsigned xb_add(unsigned* p, unsigned v) { return __hip_atomic_fetch_add(p, v, __ATOMIC_RELAXED, __HIP_MEMORY_SCOPE_AGENT); }
; #define XB_SPIN(cond, bar) do { unsigned _sp = 0; while (cond) { __builtin_amdgcn_s_sleep(1); \
;     if ((++_sp & 255u) == 0u) { if (xb_ld(&(bar)[XB_TMO])) break; if (_sp > XB_SPIN_CAP) { atomicAdd(&(bar)[XB_TMO], 1u); break; } } } } while (0)
; __device__ __forceinline__ void xcd_barrier(const XcdBarrier& b) {
;     ...
;         const unsigned old = xb_add(&bar[XB_XSUB(b.x)], 1u);
;         const unsigned gen = old / nloc;
;         if (old + 1u == (gen + 1u) * nloc) {
;             __builtin_amdgcn_fence(__ATOMIC_RELEASE, "agent");
;             asm volatile("s_waitcnt vmcnt(0)" ::: "memory");
;             const unsigned og = xb_add(&bar[XB_TOP], 1u);
;             const unsigned tg = og / nx;
;             if (og + 1u == (tg + 1u) * nx) xb_add(&bar[XB_TOPGEN], 1u);
;             else XB_SPIN(xb_ld(&bar[XB_TOPGEN]) == tg, bar);
;             __builtin_amdgcn_fence(__ATOMIC_ACQUIRE, "agent");
;             xb_add(&bar[XB_XGEN(b.x)], 1u);
;             asm volatile("s_waitcnt vmcnt(0)" ::: "memory");
;         } else {
;             XB_SPIN(xb_ld(&bar[XB_XGEN(b.x)]) == gen, bar);
.LBB0_83:
	s_or_b64 exec, exec, s[8:9]
	v_cvt_f32_u32_e32 v5, v3
	s_waitcnt vmcnt(0)
	v_readfirstlane_b32 s0, v4
	v_sub_u32_e32 v4, 0, v3
	v_rcp_iflag_f32_e32 v5, v5
	v_add_u32_e32 v6, s0, v2
	v_mul_f32_e32 v5, 0x4f7ffffe, v5
	v_cvt_u32_f32_e32 v5, v5
	v_mul_lo_u32 v2, v4, v5
	v_mul_hi_u32 v2, v5, v2
	v_add_u32_e32 v2, v5, v2
	v_mul_hi_u32 v2, v6, v2
	v_mul_lo_u32 v4, v2, v3
	v_sub_u32_e32 v4, v6, v4
	v_add_u32_e32 v5, 1, v2
	v_cmp_ge_u32_e32 vcc, v4, v3
	s_nop 1
	v_cndmask_b32_e32 v2, v2, v5, vcc
	v_sub_u32_e32 v5, v4, v3
	v_cndmask_b32_e32 v4, v4, v5, vcc
	v_add_u32_e32 v5, 1, v2
	v_cmp_ge_u32_e32 vcc, v4, v3
	v_add_u32_e32 v4, 1, v6
	s_nop 0
	v_cndmask_b32_e32 v2, v2, v5, vcc
	v_mul_lo_u32 v5, v3, v2
	v_add_u32_e32 v3, v5, v3
	v_cmp_ne_u32_e32 vcc, v4, v3
	s_and_saveexec_b64 s[0:1], vcc
	s_xor_b64 s[4:5], exec, s[0:1]
	s_cbranch_execz .LBB0_97
	s_waitcnt lgkmcnt(0)
	v_mov_b32_e32 v1, 0x7100
	global_load_dword v1, v1, s[68:69] offset:1024 sc1
	s_add_u32 s12, s68, 0x7500
	s_addc_u32 s13, s69, 0
	s_waitcnt vmcnt(0)
	v_cmp_eq_u32_e32 vcc, v1, v2
	s_and_saveexec_b64 s[8:9], vcc
	s_cbranch_execz .LBB0_96
	s_add_u32 s10, s68, 0x4200
	s_addc_u32 s11, s69, 0
	s_mov_b32 s0, 1
	s_mov_b64 s[14:15], 0
	v_mov_b32_e32 v1, 0
	s_branch .LBB0_87

; __device__ __forceinline__ unsigned xb_ld(unsigned* p)              { return __hip_atomic_load(p, __ATOMIC_RELAXED, __HIP_MEMORY_SCOPE_AGENT); }
; __device__ __forceinline__ unsigned xb_add(unsigned* p, unsigned v) { return __hip_atomic_fetch_add(p, v, __ATOMIC_RELAXED, __HIP_MEMORY_SCOPE_AGENT); }
; #define XB_SPIN(cond, bar) do { unsigned _sp = 0; while (cond) { __builtin_amdgcn_s_sleep(1); \
;     if ((++_sp & 255u) == 0u) { if (xb_ld(&(bar)[XB_TMO])) break; if (_sp > XB_SPIN_CAP) { atomicAdd(&(bar)[XB_TMO], 1u); break; } } } } while (0)
; __device__ __forceinline__ void xcd_barrier(const XcdBarrier& b) {
;     ...
;         const unsigned old = xb_add(&bar[XB_XSUB(b.x)], 1u);
;         const unsigned gen = old / nloc;
;         if (old + 1u == (gen + 1u) * nloc) {
;             __builtin_amdgcn_fence(__ATOMIC_RELEASE, "agent");
;             asm volatile("s_waitcnt vmcnt(0)" ::: "memory");
;             const unsigned og = xb_add(&bar[XB_TOP], 1u);
;             const unsigned tg = og / nx;
;             if (og + 1u == (tg + 1u) * nx) xb_add(&bar[XB_TOPGEN], 1u);
;             else XB_SPIN(xb_ld(&bar[XB_TOPGEN]) == tg, bar);
;             __builtin_amdgcn_fence(__ATOMIC_ACQUIRE, "agent");
;             xb_add(&bar[XB_XGEN(b.x)], 1u);
;             asm volatile("s_waitcnt vmcnt(0)" ::: "memory");
;         } else {
;             XB_SPIN(xb_ld(&bar[XB_XGEN(b.x)]) == gen, bar);
.LBB0_500:
	s_or_b64 exec, exec, s[8:9]
	v_cvt_f32_u32_e32 v5, v3
	s_waitcnt vmcnt(0)
	v_readfirstlane_b32 s0, v4
	v_sub_u32_e32 v4, 0, v3
	v_rcp_iflag_f32_e32 v5, v5
	v_add_u32_e32 v6, s0, v2
	v_mul_f32_e32 v5, 0x4f7ffffe, v5
	v_cvt_u32_f32_e32 v5, v5
	v_mul_lo_u32 v2, v4, v5
	v_mul_hi_u32 v2, v5, v2
	v_add_u32_e32 v2, v5, v2
	v_mul_hi_u32 v2, v6, v2
	v_mul_lo_u32 v4, v2, v3
	v_sub_u32_e32 v4, v6, v4
	v_add_u32_e32 v5, 1, v2
	v_cmp_ge_u32_e32 vcc, v4, v3
	s_nop 1
	v_cndmask_b32_e32 v2, v2, v5, vcc
	v_sub_u32_e32 v5, v4, v3
	v_cndmask_b32_e32 v4, v4, v5, vcc
	v_add_u32_e32 v5, 1, v2
	v_cmp_ge_u32_e32 vcc, v4, v3
	v_add_u32_e32 v4, 1, v6
	s_nop 0
	v_cndmask_b32_e32 v2, v2, v5, vcc
	v_mul_lo_u32 v5, v3, v2
	v_add_u32_e32 v3, v5, v3
	v_cmp_ne_u32_e32 vcc, v4, v3
	s_and_saveexec_b64 s[4:5], vcc
	s_xor_b64 s[4:5], exec, s[4:5]
	s_cbranch_execz .LBB0_514
	s_waitcnt lgkmcnt(0)
	v_mov_b32_e32 v1, 0x7100
	global_load_dword v1, v1, s[68:69] offset:1024 sc1
	s_add_u32 s12, s68, 0x7500
	s_addc_u32 s13, s69, 0
	s_waitcnt vmcnt(0)
	v_cmp_eq_u32_e32 vcc, v1, v2
	s_and_saveexec_b64 s[8:9], vcc
	s_cbranch_execz .LBB0_513
	s_add_u32 s10, s68, 0x4200
	s_addc_u32 s11, s69, 0
	s_mov_b32 s0, 1
	s_mov_b64 s[14:15], 0
	v_mov_b32_e32 v1, 0
	s_branch .LBB0_504

; __device__ __forceinline__ unsigned xb_ld(unsigned* p)              { return __hip_atomic_load(p, __ATOMIC_RELAXED, __HIP_MEMORY_SCOPE_AGENT); }
; __device__ __forceinline__ unsigned xb_add(unsigned* p, unsigned v) { return __hip_atomic_fetch_add(p, v, __ATOMIC_RELAXED, __HIP_MEMORY_SCOPE_AGENT); }
; #define XB_SPIN(cond, bar) do { unsigned _sp = 0; while (cond) { __builtin_amdgcn_s_sleep(1); \
;     if ((++_sp & 255u) == 0u) { if (xb_ld(&(bar)[XB_TMO])) break; if (_sp > XB_SPIN_CAP) { atomicAdd(&(bar)[XB_TMO], 1u); break; } } } } while (0)
; __device__ __forceinline__ void xcd_barrier(const XcdBarrier& b) {
;     ...
;         const unsigned old = xb_add(&bar[XB_XSUB(b.x)], 1u);
;         const unsigned gen = old / nloc;
;         if (old + 1u == (gen + 1u) * nloc) {
;             __builtin_amdgcn_fence(__ATOMIC_RELEASE, "agent");
;             asm volatile("s_waitcnt vmcnt(0)" ::: "memory");
;             const unsigned og = xb_add(&bar[XB_TOP], 1u);
;             const unsigned tg = og / nx;
;             if (og + 1u == (tg + 1u) * nx) xb_add(&bar[XB_TOPGEN], 1u);
;             else XB_SPIN(xb_ld(&bar[XB_TOPGEN]) == tg, bar);
;             __builtin_amdgcn_fence(__ATOMIC_ACQUIRE, "agent");
;             xb_add(&bar[XB_XGEN(b.x)], 1u);
;             asm volatile("s_waitcnt vmcnt(0)" ::: "memory");
;         } else {
;             XB_SPIN(xb_ld(&bar[XB_XGEN(b.x)]) == gen, bar);
.LBB0_564:
	s_or_b64 exec, exec, s[8:9]
	v_cvt_f32_u32_e32 v5, v3
	s_waitcnt vmcnt(0)
	v_readfirstlane_b32 s1, v4
	v_sub_u32_e32 v4, 0, v3
	v_rcp_iflag_f32_e32 v5, v5
	v_add_u32_e32 v6, s1, v2
	v_mul_f32_e32 v5, 0x4f7ffffe, v5
	v_cvt_u32_f32_e32 v5, v5
	v_mul_lo_u32 v2, v4, v5
	v_mul_hi_u32 v2, v5, v2
	v_add_u32_e32 v2, v5, v2
	v_mul_hi_u32 v2, v6, v2
	v_mul_lo_u32 v4, v2, v3
	v_sub_u32_e32 v4, v6, v4
	v_add_u32_e32 v5, 1, v2
	v_cmp_ge_u32_e32 vcc, v4, v3
	s_nop 1
	v_cndmask_b32_e32 v2, v2, v5, vcc
	v_sub_u32_e32 v5, v4, v3
	v_cndmask_b32_e32 v4, v4, v5, vcc
	v_add_u32_e32 v5, 1, v2
	v_cmp_ge_u32_e32 vcc, v4, v3
	v_add_u32_e32 v4, 1, v6
	s_nop 0
	v_cndmask_b32_e32 v2, v2, v5, vcc
	v_mul_lo_u32 v5, v3, v2
	v_add_u32_e32 v3, v5, v3
	v_cmp_ne_u32_e32 vcc, v4, v3
	s_and_saveexec_b64 s[4:5], vcc
	s_xor_b64 s[4:5], exec, s[4:5]
	s_cbranch_execz .LBB0_578
	s_waitcnt lgkmcnt(0)
	v_mov_b32_e32 v1, 0x7100
	global_load_dword v1, v1, s[68:69] offset:1024 sc1
	s_add_u32 s12, s68, 0x7500
	s_addc_u32 s13, s69, 0
	s_waitcnt vmcnt(0)
	v_cmp_eq_u32_e32 vcc, v1, v2
	s_and_saveexec_b64 s[8:9], vcc
	s_cbranch_execz .LBB0_577
	s_add_u32 s10, s68, 0x4200
	s_addc_u32 s11, s69, 0
	s_mov_b32 s1, 1
	s_mov_b64 s[14:15], 0
	v_mov_b32_e32 v1, 0
	s_branch .LBB0_568

; __device__ __forceinline__ unsigned xb_ld(unsigned* p)              { return __hip_atomic_load(p, __ATOMIC_RELAXED, __HIP_MEMORY_SCOPE_AGENT); }
; __device__ __forceinline__ unsigned xb_add(unsigned* p, unsigned v) { return __hip_atomic_fetch_add(p, v, __ATOMIC_RELAXED, __HIP_MEMORY_SCOPE_AGENT); }
; #define XB_SPIN(cond, bar) do { unsigned _sp = 0; while (cond) { __builtin_amdgcn_s_sleep(1); \
;     if ((++_sp & 255u) == 0u) { if (xb_ld(&(bar)[XB_TMO])) break; if (_sp > XB_SPIN_CAP) { atomicAdd(&(bar)[XB_TMO], 1u); break; } } } } while (0)
; __device__ __forceinline__ void xcd_barrier(const XcdBarrier& b) {
;     ...
;         const unsigned old = xb_add(&bar[XB_XSUB(b.x)], 1u);
;         const unsigned gen = old / nloc;
;         if (old + 1u == (gen + 1u) * nloc) {
;             __builtin_amdgcn_fence(__ATOMIC_RELEASE, "agent");
;             asm volatile("s_waitcnt vmcnt(0)" ::: "memory");
;             const unsigned og = xb_add(&bar[XB_TOP], 1u);
;             const unsigned tg = og / nx;
;             if (og + 1u == (tg + 1u) * nx) xb_add(&bar[XB_TOPGEN], 1u);
;             else XB_SPIN(xb_ld(&bar[XB_TOPGEN]) == tg, bar);
;             __builtin_amdgcn_fence(__ATOMIC_ACQUIRE, "agent");
;             xb_add(&bar[XB_XGEN(b.x)], 1u);
;             asm volatile("s_waitcnt vmcnt(0)" ::: "memory");
;         } else {
;             XB_SPIN(xb_ld(&bar[XB_XGEN(b.x)]) == gen, bar);
.LBB0_730:
	s_or_b64 exec, exec, s[8:9]
	v_cvt_f32_u32_e32 v5, v3
	s_waitcnt vmcnt(0)
	v_readfirstlane_b32 s4, v4
	v_sub_u32_e32 v4, 0, v3
	v_rcp_iflag_f32_e32 v5, v5
	v_add_u32_e32 v6, s4, v2
	v_mul_f32_e32 v5, 0x4f7ffffe, v5
	v_cvt_u32_f32_e32 v5, v5
	v_mul_lo_u32 v2, v4, v5
	v_mul_hi_u32 v2, v5, v2
	v_add_u32_e32 v2, v5, v2
	v_mul_hi_u32 v2, v6, v2
	v_mul_lo_u32 v4, v2, v3
	v_sub_u32_e32 v4, v6, v4
	v_add_u32_e32 v5, 1, v2
	v_cmp_ge_u32_e32 vcc, v4, v3
	s_nop 1
	v_cndmask_b32_e32 v2, v2, v5, vcc
	v_sub_u32_e32 v5, v4, v3
	v_cndmask_b32_e32 v4, v4, v5, vcc
	v_add_u32_e32 v5, 1, v2
	v_cmp_ge_u32_e32 vcc, v4, v3
	v_add_u32_e32 v4, 1, v6
	s_nop 0
	v_cndmask_b32_e32 v2, v2, v5, vcc
	v_mul_lo_u32 v5, v3, v2
	v_add_u32_e32 v3, v5, v3
	v_cmp_ne_u32_e32 vcc, v4, v3
	s_and_saveexec_b64 s[4:5], vcc
	s_xor_b64 s[4:5], exec, s[4:5]
	s_cbranch_execz .LBB0_744
	s_waitcnt lgkmcnt(0)
	v_mov_b32_e32 v1, 0x7100
	global_load_dword v1, v1, s[68:69] offset:1024 sc1
	s_add_u32 s12, s68, 0x7500
	s_addc_u32 s13, s69, 0
	s_waitcnt vmcnt(0)
	v_cmp_eq_u32_e32 vcc, v1, v2
	s_and_saveexec_b64 s[8:9], vcc
	s_cbranch_execz .LBB0_743
	s_add_u32 s10, s68, 0x4200
	s_addc_u32 s11, s69, 0
	s_mov_b32 s24, 1
	s_mov_b64 s[14:15], 0
	v_mov_b32_e32 v1, 0
	s_branch .LBB0_734

; __device__ __forceinline__ unsigned xb_ld(unsigned* p)              { return __hip_atomic_load(p, __ATOMIC_RELAXED, __HIP_MEMORY_SCOPE_AGENT); }
; __device__ __forceinline__ unsigned xb_add(unsigned* p, unsigned v) { return __hip_atomic_fetch_add(p, v, __ATOMIC_RELAXED, __HIP_MEMORY_SCOPE_AGENT); }
; #define XB_SPIN(cond, bar) do { unsigned _sp = 0; while (cond) { __builtin_amdgcn_s_sleep(1); \
;     if ((++_sp & 255u) == 0u) { if (xb_ld(&(bar)[XB_TMO])) break; if (_sp > XB_SPIN_CAP) { atomicAdd(&(bar)[XB_TMO], 1u); break; } } } } while (0)
; __device__ __forceinline__ void xcd_barrier(const XcdBarrier& b) {
;     ...
;         const unsigned old = xb_add(&bar[XB_XSUB(b.x)], 1u);
;         const unsigned gen = old / nloc;
;         if (old + 1u == (gen + 1u) * nloc) {
;             __builtin_amdgcn_fence(__ATOMIC_RELEASE, "agent");
;             asm volatile("s_waitcnt vmcnt(0)" ::: "memory");
;             const unsigned og = xb_add(&bar[XB_TOP], 1u);
;             const unsigned tg = og / nx;
;             if (og + 1u == (tg + 1u) * nx) xb_add(&bar[XB_TOPGEN], 1u);
;             else XB_SPIN(xb_ld(&bar[XB_TOPGEN]) == tg, bar);
;             __builtin_amdgcn_fence(__ATOMIC_ACQUIRE, "agent");
;             xb_add(&bar[XB_XGEN(b.x)], 1u);
;             asm volatile("s_waitcnt vmcnt(0)" ::: "memory");
;         } else {
;             XB_SPIN(xb_ld(&bar[XB_XGEN(b.x)]) == gen, bar);
.LBB0_998:
	s_or_b64 exec, exec, s[8:9]
	v_cvt_f32_u32_e32 v6, v4
	s_waitcnt vmcnt(0)
	v_readfirstlane_b32 s4, v5
	v_sub_u32_e32 v5, 0, v4
	v_rcp_iflag_f32_e32 v6, v6
	v_add_u32_e32 v7, s4, v3
	v_mul_f32_e32 v6, 0x4f7ffffe, v6
	v_cvt_u32_f32_e32 v6, v6
	v_mul_lo_u32 v3, v5, v6
	v_mul_hi_u32 v3, v6, v3
	v_add_u32_e32 v3, v6, v3
	v_mul_hi_u32 v3, v7, v3
	v_mul_lo_u32 v5, v3, v4
	v_sub_u32_e32 v5, v7, v5
	v_add_u32_e32 v6, 1, v3
	v_cmp_ge_u32_e32 vcc, v5, v4
	s_nop 1
	v_cndmask_b32_e32 v3, v3, v6, vcc
	v_sub_u32_e32 v6, v5, v4
	v_cndmask_b32_e32 v5, v5, v6, vcc
	v_add_u32_e32 v6, 1, v3
	v_cmp_ge_u32_e32 vcc, v5, v4
	v_add_u32_e32 v5, 1, v7
	s_nop 0
	v_cndmask_b32_e32 v3, v3, v6, vcc
	v_mul_lo_u32 v6, v4, v3
	v_add_u32_e32 v4, v6, v4
	v_cmp_ne_u32_e32 vcc, v5, v4
	s_and_saveexec_b64 s[4:5], vcc
	s_xor_b64 s[4:5], exec, s[4:5]
	s_cbranch_execz .LBB0_1012
	s_waitcnt lgkmcnt(0)
	v_mov_b32_e32 v2, 0x7100
	global_load_dword v2, v2, s[68:69] offset:1024 sc1
	s_add_u32 s12, s68, 0x7500
	s_addc_u32 s13, s69, 0
	s_waitcnt vmcnt(0)
	v_cmp_eq_u32_e32 vcc, v2, v3
	s_and_saveexec_b64 s[8:9], vcc
	s_cbranch_execz .LBB0_1011
	s_add_u32 s10, s68, 0x4200
	s_addc_u32 s11, s69, 0
	s_mov_b32 s24, 1
	s_mov_b64 s[14:15], 0
	v_mov_b32_e32 v2, 0
	s_branch .LBB0_1002

; __device__ __forceinline__ unsigned xb_ld(unsigned* p)              { return __hip_atomic_load(p, __ATOMIC_RELAXED, __HIP_MEMORY_SCOPE_AGENT); }
; __device__ __forceinline__ unsigned xb_add(unsigned* p, unsigned v) { return __hip_atomic_fetch_add(p, v, __ATOMIC_RELAXED, __HIP_MEMORY_SCOPE_AGENT); }
; #define XB_SPIN(cond, bar) do { unsigned _sp = 0; while (cond) { __builtin_amdgcn_s_sleep(1); \
;     if ((++_sp & 255u) == 0u) { if (xb_ld(&(bar)[XB_TMO])) break; if (_sp > XB_SPIN_CAP) { atomicAdd(&(bar)[XB_TMO], 1u); break; } } } } while (0)
; __device__ __forceinline__ void xcd_barrier(const XcdBarrier& b) {
;     ...
;         const unsigned old = xb_add(&bar[XB_XSUB(b.x)], 1u);
;         const unsigned gen = old / nloc;
;         if (old + 1u == (gen + 1u) * nloc) {
;             __builtin_amdgcn_fence(__ATOMIC_RELEASE, "agent");
;             asm volatile("s_waitcnt vmcnt(0)" ::: "memory");
;             const unsigned og = xb_add(&bar[XB_TOP], 1u);
;             const unsigned tg = og / nx;
;             if (og + 1u == (tg + 1u) * nx) xb_add(&bar[XB_TOPGEN], 1u);
;             else XB_SPIN(xb_ld(&bar[XB_TOPGEN]) == tg, bar);
;             __builtin_amdgcn_fence(__ATOMIC_ACQUIRE, "agent");
;             xb_add(&bar[XB_XGEN(b.x)], 1u);
;             asm volatile("s_waitcnt vmcnt(0)" ::: "memory");
;         } else {
;             XB_SPIN(xb_ld(&bar[XB_XGEN(b.x)]) == gen, bar);
.LBB0_1062:
	s_or_b64 exec, exec, s[8:9]
	v_cvt_f32_u32_e32 v6, v4
	s_waitcnt vmcnt(0)
	v_readfirstlane_b32 s4, v5
	v_sub_u32_e32 v5, 0, v4
	v_rcp_iflag_f32_e32 v6, v6
	v_add_u32_e32 v7, s4, v3
	v_mul_f32_e32 v6, 0x4f7ffffe, v6
	v_cvt_u32_f32_e32 v6, v6
	v_mul_lo_u32 v3, v5, v6
	v_mul_hi_u32 v3, v6, v3
	v_add_u32_e32 v3, v6, v3
	v_mul_hi_u32 v3, v7, v3
	v_mul_lo_u32 v5, v3, v4
	v_sub_u32_e32 v5, v7, v5
	v_add_u32_e32 v6, 1, v3
	v_cmp_ge_u32_e32 vcc, v5, v4
	s_nop 1
	v_cndmask_b32_e32 v3, v3, v6, vcc
	v_sub_u32_e32 v6, v5, v4
	v_cndmask_b32_e32 v5, v5, v6, vcc
	v_add_u32_e32 v6, 1, v3
	v_cmp_ge_u32_e32 vcc, v5, v4
	v_add_u32_e32 v5, 1, v7
	s_nop 0
	v_cndmask_b32_e32 v3, v3, v6, vcc
	v_mul_lo_u32 v6, v4, v3
	v_add_u32_e32 v4, v6, v4
	v_cmp_ne_u32_e32 vcc, v5, v4
	s_and_saveexec_b64 s[4:5], vcc
	s_xor_b64 s[4:5], exec, s[4:5]
	s_cbranch_execz .LBB0_1076
	s_waitcnt lgkmcnt(0)
	v_mov_b32_e32 v2, 0x7100
	global_load_dword v2, v2, s[68:69] offset:1024 sc1
	s_add_u32 s14, s68, 0x7500
	s_addc_u32 s15, s69, 0
	s_waitcnt vmcnt(0)
	v_cmp_eq_u32_e32 vcc, v2, v3
	s_and_saveexec_b64 s[8:9], vcc
	s_cbranch_execz .LBB0_1075
	s_add_u32 s10, s68, 0x4200
	s_addc_u32 s11, s69, 0
	s_mov_b32 s26, 1
	s_mov_b64 s[16:17], 0
	v_mov_b32_e32 v2, 0
	s_branch .LBB0_1066

; __device__ __forceinline__ unsigned xb_ld(unsigned* p)              { return __hip_atomic_load(p, __ATOMIC_RELAXED, __HIP_MEMORY_SCOPE_AGENT); }
; __device__ __forceinline__ unsigned xb_add(unsigned* p, unsigned v) { return __hip_atomic_fetch_add(p, v, __ATOMIC_RELAXED, __HIP_MEMORY_SCOPE_AGENT); }
; #define XB_SPIN(cond, bar) do { unsigned _sp = 0; while (cond) { __builtin_amdgcn_s_sleep(1); \
;     if ((++_sp & 255u) == 0u) { if (xb_ld(&(bar)[XB_TMO])) break; if (_sp > XB_SPIN_CAP) { atomicAdd(&(bar)[XB_TMO], 1u); break; } } } } while (0)
; __device__ __forceinline__ void xcd_barrier(const XcdBarrier& b) {
;     ...
;         const unsigned old = xb_add(&bar[XB_XSUB(b.x)], 1u);
;         const unsigned gen = old / nloc;
;         if (old + 1u == (gen + 1u) * nloc) {
;             __builtin_amdgcn_fence(__ATOMIC_RELEASE, "agent");
;             asm volatile("s_waitcnt vmcnt(0)" ::: "memory");
;             const unsigned og = xb_add(&bar[XB_TOP], 1u);
;             const unsigned tg = og / nx;
;             if (og + 1u == (tg + 1u) * nx) xb_add(&bar[XB_TOPGEN], 1u);
;             else XB_SPIN(xb_ld(&bar[XB_TOPGEN]) == tg, bar);
;             __builtin_amdgcn_fence(__ATOMIC_ACQUIRE, "agent");
;             xb_add(&bar[XB_XGEN(b.x)], 1u);
;             asm volatile("s_waitcnt vmcnt(0)" ::: "memory");
;         } else {
;             XB_SPIN(xb_ld(&bar[XB_XGEN(b.x)]) == gen, bar);
.LBB0_1253:
	s_or_b64 exec, exec, s[8:9]
	v_cvt_f32_u32_e32 v6, v4
	s_waitcnt vmcnt(0)
	v_readfirstlane_b32 s1, v5
	v_sub_u32_e32 v5, 0, v4
	v_rcp_iflag_f32_e32 v6, v6
	v_add_u32_e32 v7, s1, v3
	v_mul_f32_e32 v6, 0x4f7ffffe, v6
	v_cvt_u32_f32_e32 v6, v6
	v_mul_lo_u32 v3, v5, v6
	v_mul_hi_u32 v3, v6, v3
	v_add_u32_e32 v3, v6, v3
	v_mul_hi_u32 v3, v7, v3
	v_mul_lo_u32 v5, v3, v4
	v_sub_u32_e32 v5, v7, v5
	v_add_u32_e32 v6, 1, v3
	v_cmp_ge_u32_e32 vcc, v5, v4
	s_nop 1
	v_cndmask_b32_e32 v3, v3, v6, vcc
	v_sub_u32_e32 v6, v5, v4
	v_cndmask_b32_e32 v5, v5, v6, vcc
	v_add_u32_e32 v6, 1, v3
	v_cmp_ge_u32_e32 vcc, v5, v4
	v_add_u32_e32 v5, 1, v7
	s_nop 0
	v_cndmask_b32_e32 v3, v3, v6, vcc
	v_mul_lo_u32 v6, v4, v3
	v_add_u32_e32 v4, v6, v4
	v_cmp_ne_u32_e32 vcc, v5, v4
	s_and_saveexec_b64 s[4:5], vcc
	s_xor_b64 s[4:5], exec, s[4:5]
	s_cbranch_execz .LBB0_1267
	s_waitcnt lgkmcnt(0)
	v_mov_b32_e32 v2, 0x7100
	global_load_dword v2, v2, s[68:69] offset:1024 sc1
	s_add_u32 s12, s68, 0x7500
	s_addc_u32 s13, s69, 0
	s_waitcnt vmcnt(0)
	v_cmp_eq_u32_e32 vcc, v2, v3
	s_and_saveexec_b64 s[8:9], vcc
	s_cbranch_execz .LBB0_1266
	s_add_u32 s10, s68, 0x4200
	s_addc_u32 s11, s69, 0
	s_mov_b32 s1, 1
	s_mov_b64 s[14:15], 0
	v_mov_b32_e32 v2, 0
	s_branch .LBB0_1257

; __device__ __forceinline__ unsigned xb_ld(unsigned* p)              { return __hip_atomic_load(p, __ATOMIC_RELAXED, __HIP_MEMORY_SCOPE_AGENT); }
; __device__ __forceinline__ unsigned xb_add(unsigned* p, unsigned v) { return __hip_atomic_fetch_add(p, v, __ATOMIC_RELAXED, __HIP_MEMORY_SCOPE_AGENT); }
; #define XB_SPIN(cond, bar) do { unsigned _sp = 0; while (cond) { __builtin_amdgcn_s_sleep(1); \
;     if ((++_sp & 255u) == 0u) { if (xb_ld(&(bar)[XB_TMO])) break; if (_sp > XB_SPIN_CAP) { atomicAdd(&(bar)[XB_TMO], 1u); break; } } } } while (0)
; __device__ __forceinline__ void xcd_barrier(const XcdBarrier& b) {
;     ...
;         const unsigned old = xb_add(&bar[XB_XSUB(b.x)], 1u);
;         const unsigned gen = old / nloc;
;         if (old + 1u == (gen + 1u) * nloc) {
;             __builtin_amdgcn_fence(__ATOMIC_RELEASE, "agent");
;             asm volatile("s_waitcnt vmcnt(0)" ::: "memory");
;             const unsigned og = xb_add(&bar[XB_TOP], 1u);
;             const unsigned tg = og / nx;
;             if (og + 1u == (tg + 1u) * nx) xb_add(&bar[XB_TOPGEN], 1u);
;             else XB_SPIN(xb_ld(&bar[XB_TOPGEN]) == tg, bar);
;             __builtin_amdgcn_fence(__ATOMIC_ACQUIRE, "agent");
;             xb_add(&bar[XB_XGEN(b.x)], 1u);
;             asm volatile("s_waitcnt vmcnt(0)" ::: "memory");
;         } else {
;             XB_SPIN(xb_ld(&bar[XB_XGEN(b.x)]) == gen, bar);
.LBB0_1740:
	s_or_b64 exec, exec, s[8:9]
	v_cvt_f32_u32_e32 v5, v3
	s_waitcnt vmcnt(0)
	v_readfirstlane_b32 s1, v4
	v_sub_u32_e32 v4, 0, v3
	v_rcp_iflag_f32_e32 v5, v5
	v_add_u32_e32 v6, s1, v2
	v_mul_f32_e32 v5, 0x4f7ffffe, v5
	v_cvt_u32_f32_e32 v5, v5
	v_mul_lo_u32 v2, v4, v5
	v_mul_hi_u32 v2, v5, v2
	v_add_u32_e32 v2, v5, v2
	v_mul_hi_u32 v2, v6, v2
	v_mul_lo_u32 v4, v2, v3
	v_sub_u32_e32 v4, v6, v4
	v_add_u32_e32 v5, 1, v2
	v_cmp_ge_u32_e32 vcc, v4, v3
	s_nop 1
	v_cndmask_b32_e32 v2, v2, v5, vcc
	v_sub_u32_e32 v5, v4, v3
	v_cndmask_b32_e32 v4, v4, v5, vcc
	v_add_u32_e32 v5, 1, v2
	v_cmp_ge_u32_e32 vcc, v4, v3
	v_add_u32_e32 v4, 1, v6
	s_nop 0
	v_cndmask_b32_e32 v2, v2, v5, vcc
	v_mul_lo_u32 v5, v3, v2
	v_add_u32_e32 v3, v5, v3
	v_cmp_ne_u32_e32 vcc, v4, v3
	s_and_saveexec_b64 s[4:5], vcc
	s_xor_b64 s[4:5], exec, s[4:5]
	s_cbranch_execz .LBB0_1754
	s_waitcnt lgkmcnt(0)
	v_mov_b32_e32 v1, 0x7100
	global_load_dword v1, v1, s[68:69] offset:1024 sc1
	s_add_u32 s14, s68, 0x7500
	s_addc_u32 s15, s69, 0
	s_waitcnt vmcnt(0)
	v_cmp_eq_u32_e32 vcc, v1, v2
	s_and_saveexec_b64 s[8:9], vcc
	s_cbranch_execz .LBB0_1753
	s_add_u32 s10, s68, 0x4200
	s_addc_u32 s11, s69, 0
	s_mov_b32 s1, 1
	s_mov_b64 s[16:17], 0
	v_mov_b32_e32 v1, 0
	s_branch .LBB0_1744

; __device__ __forceinline__ unsigned xb_ld(unsigned* p)              { return __hip_atomic_load(p, __ATOMIC_RELAXED, __HIP_MEMORY_SCOPE_AGENT); }
; __device__ __forceinline__ unsigned xb_add(unsigned* p, unsigned v) { return __hip_atomic_fetch_add(p, v, __ATOMIC_RELAXED, __HIP_MEMORY_SCOPE_AGENT); }
; #define XB_SPIN(cond, bar) do { unsigned _sp = 0; while (cond) { __builtin_amdgcn_s_sleep(1); \
;     if ((++_sp & 255u) == 0u) { if (xb_ld(&(bar)[XB_TMO])) break; if (_sp > XB_SPIN_CAP) { atomicAdd(&(bar)[XB_TMO], 1u); break; } } } } while (0)
; __device__ __forceinline__ void xcd_barrier(const XcdBarrier& b) {
;     ...
;         const unsigned old = xb_add(&bar[XB_XSUB(b.x)], 1u);
;         const unsigned gen = old / nloc;
;         if (old + 1u == (gen + 1u) * nloc) {
;             __builtin_amdgcn_fence(__ATOMIC_RELEASE, "agent");
;             asm volatile("s_waitcnt vmcnt(0)" ::: "memory");
;             const unsigned og = xb_add(&bar[XB_TOP], 1u);
;             const unsigned tg = og / nx;
;             if (og + 1u == (tg + 1u) * nx) xb_add(&bar[XB_TOPGEN], 1u);
;             else XB_SPIN(xb_ld(&bar[XB_TOPGEN]) == tg, bar);
;             __builtin_amdgcn_fence(__ATOMIC_ACQUIRE, "agent");
;             xb_add(&bar[XB_XGEN(b.x)], 1u);
;             asm volatile("s_waitcnt vmcnt(0)" ::: "memory");
;         } else {
;             XB_SPIN(xb_ld(&bar[XB_XGEN(b.x)]) == gen, bar);
.LBB0_2163:
	s_or_b64 exec, exec, s[10:11]
	v_cvt_f32_u32_e32 v5, v3
	s_waitcnt vmcnt(0)
	v_readfirstlane_b32 s1, v4
	v_sub_u32_e32 v4, 0, v3
	v_rcp_iflag_f32_e32 v5, v5
	v_add_u32_e32 v6, s1, v2
	v_mul_f32_e32 v5, 0x4f7ffffe, v5
	v_cvt_u32_f32_e32 v5, v5
	v_mul_lo_u32 v2, v4, v5
	v_mul_hi_u32 v2, v5, v2
	v_add_u32_e32 v2, v5, v2
	v_mul_hi_u32 v2, v6, v2
	v_mul_lo_u32 v4, v2, v3
	v_sub_u32_e32 v4, v6, v4
	v_add_u32_e32 v5, 1, v2
	v_cmp_ge_u32_e32 vcc, v4, v3
	s_nop 1
	v_cndmask_b32_e32 v2, v2, v5, vcc
	v_sub_u32_e32 v5, v4, v3
	v_cndmask_b32_e32 v4, v4, v5, vcc
	v_add_u32_e32 v5, 1, v2
	v_cmp_ge_u32_e32 vcc, v4, v3
	v_add_u32_e32 v4, 1, v6
	s_nop 0
	v_cndmask_b32_e32 v2, v2, v5, vcc
	v_mul_lo_u32 v5, v3, v2
	v_add_u32_e32 v3, v5, v3
	v_cmp_ne_u32_e32 vcc, v4, v3
	s_and_saveexec_b64 s[4:5], vcc
	s_xor_b64 s[4:5], exec, s[4:5]
	s_cbranch_execz .LBB0_2177
	s_waitcnt lgkmcnt(0)
	v_mov_b32_e32 v1, 0x7100
	global_load_dword v1, v1, s[68:69] offset:1024 sc1
	s_add_u32 s14, s68, 0x7500
	s_addc_u32 s15, s69, 0
	s_waitcnt vmcnt(0)
	v_cmp_eq_u32_e32 vcc, v1, v2
	s_and_saveexec_b64 s[10:11], vcc
	s_cbranch_execz .LBB0_2176
	s_add_u32 s12, s68, 0x4200
	s_addc_u32 s13, s69, 0
	s_mov_b32 s1, 1
	s_mov_b64 s[16:17], 0
	v_mov_b32_e32 v1, 0
	s_branch .LBB0_2167

; __device__ __forceinline__ unsigned xb_ld(unsigned* p)              { return __hip_atomic_load(p, __ATOMIC_RELAXED, __HIP_MEMORY_SCOPE_AGENT); }
; __device__ __forceinline__ unsigned xb_add(unsigned* p, unsigned v) { return __hip_atomic_fetch_add(p, v, __ATOMIC_RELAXED, __HIP_MEMORY_SCOPE_AGENT); }
; #define XB_SPIN(cond, bar) do { unsigned _sp = 0; while (cond) { __builtin_amdgcn_s_sleep(1); \
;     if ((++_sp & 255u) == 0u) { if (xb_ld(&(bar)[XB_TMO])) break; if (_sp > XB_SPIN_CAP) { atomicAdd(&(bar)[XB_TMO], 1u); break; } } } } while (0)
; __device__ __forceinline__ void xcd_barrier(const XcdBarrier& b) {
;     ...
;         const unsigned old = xb_add(&bar[XB_XSUB(b.x)], 1u);
;         const unsigned gen = old / nloc;
;         if (old + 1u == (gen + 1u) * nloc) {
;             __builtin_amdgcn_fence(__ATOMIC_RELEASE, "agent");
;             asm volatile("s_waitcnt vmcnt(0)" ::: "memory");
;             const unsigned og = xb_add(&bar[XB_TOP], 1u);
;             const unsigned tg = og / nx;
;             if (og + 1u == (tg + 1u) * nx) xb_add(&bar[XB_TOPGEN], 1u);
;             else XB_SPIN(xb_ld(&bar[XB_TOPGEN]) == tg, bar);
;             __builtin_amdgcn_fence(__ATOMIC_ACQUIRE, "agent");
;             xb_add(&bar[XB_XGEN(b.x)], 1u);
;             asm volatile("s_waitcnt vmcnt(0)" ::: "memory");
;         } else {
;             XB_SPIN(xb_ld(&bar[XB_XGEN(b.x)]) == gen, bar);
.LBB0_2288:
	s_or_b64 exec, exec, s[10:11]
	v_cvt_f32_u32_e32 v5, v3
	s_waitcnt vmcnt(0)
	v_readfirstlane_b32 s4, v4
	v_sub_u32_e32 v4, 0, v3
	v_rcp_iflag_f32_e32 v5, v5
	v_add_u32_e32 v6, s4, v2
	v_mul_f32_e32 v5, 0x4f7ffffe, v5
	v_cvt_u32_f32_e32 v5, v5
	v_mul_lo_u32 v2, v4, v5
	v_mul_hi_u32 v2, v5, v2
	v_add_u32_e32 v2, v5, v2
	v_mul_hi_u32 v2, v6, v2
	v_mul_lo_u32 v4, v2, v3
	v_sub_u32_e32 v4, v6, v4
	v_add_u32_e32 v5, 1, v2
	v_cmp_ge_u32_e32 vcc, v4, v3
	s_nop 1
	v_cndmask_b32_e32 v2, v2, v5, vcc
	v_sub_u32_e32 v5, v4, v3
	v_cndmask_b32_e32 v4, v4, v5, vcc
	v_add_u32_e32 v5, 1, v2
	v_cmp_ge_u32_e32 vcc, v4, v3
	v_add_u32_e32 v4, 1, v6
	s_nop 0
	v_cndmask_b32_e32 v2, v2, v5, vcc
	v_mul_lo_u32 v5, v3, v2
	v_add_u32_e32 v3, v5, v3
	v_cmp_ne_u32_e32 vcc, v4, v3
	s_and_saveexec_b64 s[4:5], vcc
	s_xor_b64 s[4:5], exec, s[4:5]
	s_cbranch_execz .LBB0_2302
	s_waitcnt lgkmcnt(0)
	v_mov_b32_e32 v1, 0x7100
	global_load_dword v1, v1, s[68:69] offset:1024 sc1
	s_add_u32 s14, s68, 0x7500
	s_addc_u32 s15, s69, 0
	s_waitcnt vmcnt(0)
	v_cmp_eq_u32_e32 vcc, v1, v2
	s_and_saveexec_b64 s[10:11], vcc
	s_cbranch_execz .LBB0_2301
	s_add_u32 s12, s68, 0x4200
	s_addc_u32 s13, s69, 0
	s_mov_b32 s26, 1
	s_mov_b64 s[16:17], 0
	v_mov_b32_e32 v1, 0
	s_branch .LBB0_2292

; __device__ __forceinline__ unsigned xb_ld(unsigned* p)              { return __hip_atomic_load(p, __ATOMIC_RELAXED, __HIP_MEMORY_SCOPE_AGENT); }
; __device__ __forceinline__ unsigned xb_add(unsigned* p, unsigned v) { return __hip_atomic_fetch_add(p, v, __ATOMIC_RELAXED, __HIP_MEMORY_SCOPE_AGENT); }
; #define XB_SPIN(cond, bar) do { unsigned _sp = 0; while (cond) { __builtin_amdgcn_s_sleep(1); \
;     if ((++_sp & 255u) == 0u) { if (xb_ld(&(bar)[XB_TMO])) break; if (_sp > XB_SPIN_CAP) { atomicAdd(&(bar)[XB_TMO], 1u); break; } } } } while (0)
; __device__ __forceinline__ void xcd_barrier(const XcdBarrier& b) {
;     ...
;         const unsigned old = xb_add(&bar[XB_XSUB(b.x)], 1u);
;         const unsigned gen = old / nloc;
;         if (old + 1u == (gen + 1u) * nloc) {
;             __builtin_amdgcn_fence(__ATOMIC_RELEASE, "agent");
;             asm volatile("s_waitcnt vmcnt(0)" ::: "memory");
;             const unsigned og = xb_add(&bar[XB_TOP], 1u);
;             const unsigned tg = og / nx;
;             if (og + 1u == (tg + 1u) * nx) xb_add(&bar[XB_TOPGEN], 1u);
;             else XB_SPIN(xb_ld(&bar[XB_TOPGEN]) == tg, bar);
;             __builtin_amdgcn_fence(__ATOMIC_ACQUIRE, "agent");
;             xb_add(&bar[XB_XGEN(b.x)], 1u);
;             asm volatile("s_waitcnt vmcnt(0)" ::: "memory");
;         } else {
;             XB_SPIN(xb_ld(&bar[XB_XGEN(b.x)]) == gen, bar);
.LBB0_2352:
	s_or_b64 exec, exec, s[6:7]
	v_cvt_f32_u32_e32 v5, v3
	s_waitcnt vmcnt(0)
	v_readfirstlane_b32 s0, v4
	v_sub_u32_e32 v4, 0, v3
	v_rcp_iflag_f32_e32 v5, v5
	v_add_u32_e32 v6, s0, v2
	v_mul_f32_e32 v5, 0x4f7ffffe, v5
	v_cvt_u32_f32_e32 v5, v5
	v_mul_lo_u32 v2, v4, v5
	v_mul_hi_u32 v2, v5, v2
	v_add_u32_e32 v2, v5, v2
	v_mul_hi_u32 v2, v6, v2
	v_mul_lo_u32 v4, v2, v3
	v_sub_u32_e32 v4, v6, v4
	v_add_u32_e32 v5, 1, v2
	v_cmp_ge_u32_e32 vcc, v4, v3
	s_nop 1
	v_cndmask_b32_e32 v2, v2, v5, vcc
	v_sub_u32_e32 v5, v4, v3
	v_cndmask_b32_e32 v4, v4, v5, vcc
	v_add_u32_e32 v5, 1, v2
	v_cmp_ge_u32_e32 vcc, v4, v3
	v_add_u32_e32 v4, 1, v6
	s_nop 0
	v_cndmask_b32_e32 v2, v2, v5, vcc
	v_mul_lo_u32 v5, v3, v2
	v_add_u32_e32 v3, v5, v3
	v_cmp_ne_u32_e32 vcc, v4, v3
	s_and_saveexec_b64 s[0:1], vcc
	s_xor_b64 s[0:1], exec, s[0:1]
	s_cbranch_execz .LBB0_2366
	s_waitcnt lgkmcnt(0)
	v_mov_b32_e32 v1, 0x7100
	global_load_dword v1, v1, s[68:69] offset:1024 sc1
	s_add_u32 s10, s68, 0x7500
	s_addc_u32 s11, s69, 0
	s_waitcnt vmcnt(0)
	v_cmp_eq_u32_e32 vcc, v1, v2
	s_and_saveexec_b64 s[6:7], vcc
	s_cbranch_execz .LBB0_2365
	s_add_u32 s8, s68, 0x4200
	s_addc_u32 s9, s69, 0
	s_mov_b32 s22, 1
	s_mov_b64 s[12:13], 0
	v_mov_b32_e32 v1, 0
	s_branch .LBB0_2356
